# C + GEMM K-loop heads at phase 0 + attention loop head moved from phase 4 to phase 0 (code placement scan)
# speedup vs baseline: 1.0057x; 1.0020x over previous
; #define LAS __attribute__((address_space(3)))
; __device__ __forceinline__ void attn_unit(const Params& p, LAS unsigned char* lds, int b, int h, int qb, int tid, int wid, int lane, u64& tacc, v4u& kA, v4u& vA, v4u& kB, v4u& vB, const bool first) {
;     ...
;     const u64* bmq = bm + (rowbase + q0 + wid * 32 + r32) * 64;
;     const unsigned stoff = wid * 1024 + lane * 16;
;     const unsigned vboff = 8192 + ((lane >> 4) & 1) * 32 + (lane & 3) * 8 + (4 * hi + ((lane & 15) >> 2)) * 64;
;     float m = 0.f; bool started = false; f32x16 o0, o1, o2;
; #pragma unroll
;     for (int i = 0; i < 16; ++i) { o0[i] = 0.f; o1[i] = 0.f; o2[i] = 0.f; }
;     float negv = -1e30f; asm volatile("" : "+v"(negv));
;     const bf16x8 ones8 = (bf16x8){0x3f80, 0x3f80, 0x3f80, 0x3f80, 0x3f80, 0x3f80, 0x3f80, 0x3f80};
;     v4u mwc = *(const v4u*)bmq, mwn = mwc;
;     if (first) {
;         kB = *(const v4u*)ksrc; vB = *(const v4u*)vsrc;
;         kA = *(const v4u*)(ksrc + (size_t)4096); vA = *(const v4u*)(vsrc + (size_t)4096);
;         *(LAS v4u*)(lds + stoff) = kB; *(LAS v4u*)(lds + 8192 + stoff) = vB;
;         kB = *(const v4u*)(ksrc + (size_t)2 * 4096); vB = *(const v4u*)(vsrc + (size_t)2 * 4096);
;     }
;     bf16x8 Eop[2];
; #pragma unroll
;     for (int s = 0; s < 2; ++s) { v4u e; unsigned* ep = (unsigned*)&e;
; #pragma unroll
;         for (int i = 0; i < 4; ++i) { const int k0 = 4 * s + i + 8 * hi; ep[i] = (r32 == k0 ? 0x3F80u : 0u) | (r32 == k0 + 16 ? 0x3F800000u : 0u); }
;         Eop[s] = __builtin_bit_cast(bf16x8, e); }
;     f32x16 nsplat;
; #pragma unroll
;     for (int r = 0; r < 16; ++r) nsplat[r] = -m;
.LBB0_3758:
	v_lshl_add_u64 v[2:3], v[194:195], 0, s[2:3]
	v_lshlrev_b64 v[2:3], 9, v[2:3]
	s_waitcnt vmcnt(5)
	v_mov_b32_e32 v14, v0
	v_mov_b32_e32 v15, v0
	v_lshl_add_u64 v[196:197], s[6:7], 0, v[2:3]
	v_mov_b32_e32 v1, v0
	v_mov_b32_e32 v2, v0
	v_mov_b32_e32 v3, v0
	v_mov_b32_e32 v4, v0
	v_mov_b32_e32 v5, v0
	v_mov_b32_e32 v6, v0
	v_mov_b32_e32 v7, v0
	v_mov_b32_e32 v8, v0
	v_mov_b32_e32 v9, v0
	v_mov_b32_e32 v10, v0
	v_mov_b32_e32 v11, v0
	v_mov_b32_e32 v12, v0
	v_mov_b32_e32 v13, v0
	v_mov_b32_e32 v30, v159
	v_mov_b32_e32 v31, v159
	v_mov_b64_e32 v[78:79], v[14:15]
	s_lshl_b32 s46, s0, 2
	v_mov_b32_e32 v16, v159
	v_mov_b32_e32 v17, v159
	v_mov_b32_e32 v18, v159
	v_mov_b32_e32 v19, v159
	v_mov_b32_e32 v20, v159
	v_mov_b32_e32 v21, v159
	v_mov_b32_e32 v22, v159
	v_mov_b32_e32 v23, v159
	v_mov_b32_e32 v24, v159
	v_mov_b32_e32 v25, v159
	v_mov_b32_e32 v26, v159
	v_mov_b32_e32 v27, v159
	v_mov_b32_e32 v28, v159
	v_mov_b32_e32 v29, v159
	v_mov_b64_e32 v[46:47], v[30:31]
	v_mov_b64_e32 v[62:63], v[30:31]
	v_mov_b64_e32 v[76:77], v[12:13]
	v_mov_b64_e32 v[74:75], v[10:11]
	v_mov_b64_e32 v[72:73], v[8:9]
	v_mov_b64_e32 v[70:71], v[6:7]
	v_mov_b64_e32 v[68:69], v[4:5]
	v_mov_b64_e32 v[66:67], v[2:3]
	v_mov_b64_e32 v[64:65], v[0:1]
	s_waitcnt vmcnt(0)
	v_mov_b64_e32 v[2:3], v[152:153]
	s_add_i32 s47, s46, s25
	s_add_i32 s48, s46, 4
	s_mov_b32 s51, 0
	s_sub_i32 s49, 0, s46
	s_mov_b64 s[20:21], 0
	v_mov_b32_e32 v171, 0
	v_mov_b64_e32 v[44:45], v[28:29]
	v_mov_b64_e32 v[42:43], v[26:27]
	v_mov_b64_e32 v[40:41], v[24:25]
	v_mov_b64_e32 v[38:39], v[22:23]
	v_mov_b64_e32 v[36:37], v[20:21]
	v_mov_b64_e32 v[34:35], v[18:19]
	v_mov_b64_e32 v[32:33], v[16:17]
	v_mov_b64_e32 v[60:61], v[28:29]
	v_mov_b64_e32 v[58:59], v[26:27]
	v_mov_b64_e32 v[56:57], v[24:25]
	v_mov_b64_e32 v[54:55], v[22:23]
	v_mov_b64_e32 v[52:53], v[20:21]
	v_mov_b64_e32 v[50:51], v[18:19]
	v_mov_b64_e32 v[48:49], v[16:17]
	v_mov_b64_e32 v[4:5], v[154:155]
	s_nop 0
	s_nop 0
	s_nop 0
	s_nop 0
	s_nop 0
	s_nop 0
	s_nop 0
	s_nop 0
	s_nop 0
	s_nop 0
	s_nop 0
	s_nop 0
	s_nop 0
	s_nop 0
	s_nop 0
